# C1 epilogue: 8 row-stat loads issued together (7 store-draining vmcnt(0) waits removed)
# speedup vs baseline: 1.0189x; 1.0001x over previous
.LBB0_140:
	v_lshl_add_u32 v146, s42, 8, v142
	v_ashrrev_i32_e32 v147, 31, v146
	v_lshl_add_u64 v[140:141], v[146:147], 2, s[8:9]
	global_load_dword v145, v[140:141], off
	global_load_dword v225, v[140:141], off offset:64
	global_load_dword v226, v[140:141], off offset:128
	global_load_dword v227, v[140:141], off offset:192
	global_load_dword v228, v[140:141], off offset:512
	global_load_dword v229, v[140:141], off offset:576
	global_load_dword v230, v[140:141], off offset:640
	global_load_dword v231, v[140:141], off offset:704
	v_pk_mul_f32 v[114:115], v[122:123], v[114:115]
	s_lshl_b32 s28, s41, 7
	v_pk_mul_f32 v[120:121], v[120:121], v[112:113]
	v_lshlrev_b64 v[112:113], 12, v[146:147]
	s_ashr_i32 s29, s28, 31
	v_lshl_add_u64 v[112:113], s[6:7], 0, v[112:113]
	v_lshl_add_u64 v[112:113], s[28:29], 1, v[112:113]
	v_pk_mul_f32 v[116:117], v[124:125], v[116:117]
	v_pk_mul_f32 v[118:119], v[126:127], v[118:119]
	v_lshl_add_u64 v[112:113], v[112:113], 0, s[72:73]
	v_lshl_add_u64 v[112:113], v[112:113], 0, v[176:177]
	v_pk_mul_f32 v[102:103], v[110:111], v[102:103]
	v_pk_mul_f32 v[98:99], v[106:107], v[98:99]
	v_pk_mul_f32 v[100:101], v[108:109], v[100:101]
	v_pk_mul_f32 v[96:97], v[104:105], v[96:97]
	v_pk_mul_f32 v[86:87], v[94:95], v[86:87]
	v_pk_mul_f32 v[82:83], v[90:91], v[82:83]
	v_pk_mul_f32 v[84:85], v[92:93], v[84:85]
	s_mov_b32 s45, 0x20000
	v_pk_mul_f32 v[80:81], v[88:89], v[80:81]
	v_pk_mul_f32 v[70:71], v[78:79], v[70:71]
	v_pk_mul_f32 v[66:67], v[74:75], v[66:67]
	v_pk_mul_f32 v[68:69], v[76:77], v[68:69]
	s_mov_b32 s44, 0x30000
	v_pk_mul_f32 v[64:65], v[72:73], v[64:65]
	v_pk_mul_f32 v[54:55], v[62:63], v[54:55]
	v_pk_mul_f32 v[50:51], v[58:59], v[50:51]
	v_pk_mul_f32 v[52:53], v[60:61], v[52:53]
	s_mov_b32 s13, 0x80000
	v_pk_mul_f32 v[48:49], v[56:57], v[48:49]
	v_pk_mul_f32 v[38:39], v[46:47], v[38:39]
	v_pk_mul_f32 v[34:35], v[42:43], v[34:35]
	v_pk_mul_f32 v[36:37], v[44:45], v[36:37]
	s_mov_b32 s46, 0x90000
	v_pk_mul_f32 v[32:33], v[40:41], v[32:33]
	v_pk_mul_f32 v[22:23], v[30:31], v[22:23]
	v_pk_mul_f32 v[18:19], v[26:27], v[18:19]
	v_pk_mul_f32 v[20:21], v[28:29], v[20:21]
	v_pk_mul_f32 v[16:17], v[24:25], v[16:17]
	v_pk_mul_f32 v[4:5], v[12:13], v[4:5]
	v_pk_mul_f32 v[0:1], v[8:9], v[0:1]
	v_pk_mul_f32 v[2:3], v[10:11], v[2:3]
	v_pk_mul_f32 v[6:7], v[14:15], v[6:7]
	s_mov_b32 s47, 0x3c000
	s_waitcnt vmcnt(0)
	v_cvt_f32_u32_e32 v122, v145
	v_fmamk_f32 v122, v122, 0x33000000, v213
	v_div_scale_f32 v123, s[28:29], v122, v122, 1.0
	v_rcp_f32_e32 v124, v123
	v_div_scale_f32 v125, vcc, 1.0, v122, 1.0
	v_fma_f32 v126, -v123, v124, 1.0
	v_fmac_f32_e32 v124, v126, v124
	v_mul_f32_e32 v126, v125, v124
	v_fma_f32 v127, -v123, v126, v125
	v_fmac_f32_e32 v126, v127, v124
	v_fma_f32 v123, -v123, v126, v125
	v_div_fmas_f32 v123, v123, v124, v126
	v_div_fixup_f32 v122, v123, v122, 1.0
	v_pk_mul_f32 v[118:119], v[118:119], v[122:123] op_sel_hi:[1,0]
	v_pk_mul_f32 v[116:117], v[116:117], v[122:123] op_sel_hi:[1,0]
	v_pk_mul_f32 v[124:125], v[114:115], v[122:123] op_sel_hi:[1,0]
	v_pk_mul_f32 v[120:121], v[120:121], v[122:123] op_sel_hi:[1,0]
	v_cvt_pk_bf16_f32 v114, v116, v117
	v_cvt_pk_bf16_f32 v115, v118, v119
	v_cvt_pk_bf16_f32 v116, v120, v121
	v_cvt_pk_bf16_f32 v117, v124, v125
	global_store_dwordx4 v[112:113], v[114:117], off
	v_add_co_u32_e32 v104, vcc, s91, v112
	v_cvt_f32_u32_e32 v110, v225
	v_addc_co_u32_e32 v105, vcc, 0, v113, vcc
	v_fmamk_f32 v106, v110, 0x33000000, v213
	v_div_scale_f32 v107, s[28:29], v106, v106, 1.0
	v_rcp_f32_e32 v108, v107
	v_div_scale_f32 v109, vcc, 1.0, v106, 1.0
	v_fma_f32 v110, -v107, v108, 1.0
	v_fmac_f32_e32 v108, v110, v108
	v_mul_f32_e32 v110, v109, v108
	v_fma_f32 v111, -v107, v110, v109
	v_fmac_f32_e32 v110, v111, v108
	v_fma_f32 v107, -v107, v110, v109
	v_div_fmas_f32 v107, v107, v108, v110
	v_div_fixup_f32 v106, v107, v106, 1.0
	v_pk_mul_f32 v[102:103], v[102:103], v[106:107] op_sel_hi:[1,0]
	v_pk_mul_f32 v[100:101], v[100:101], v[106:107] op_sel_hi:[1,0]
	v_pk_mul_f32 v[108:109], v[98:99], v[106:107] op_sel_hi:[1,0]
	v_pk_mul_f32 v[98:99], v[96:97], v[106:107] op_sel_hi:[1,0]
	v_cvt_pk_bf16_f32 v96, v100, v101
	v_cvt_pk_bf16_f32 v97, v102, v103
	v_cvt_pk_bf16_f32 v98, v98, v99
	v_cvt_pk_bf16_f32 v99, v108, v109
	global_store_dwordx4 v[104:105], v[96:99], off
	v_add_co_u32_e32 v88, vcc, s45, v112
	v_cvt_f32_u32_e32 v94, v226
	v_addc_co_u32_e32 v89, vcc, 0, v113, vcc
	v_fmamk_f32 v90, v94, 0x33000000, v213
	v_div_scale_f32 v91, s[28:29], v90, v90, 1.0
	v_rcp_f32_e32 v92, v91
	v_div_scale_f32 v93, vcc, 1.0, v90, 1.0
	v_fma_f32 v94, -v91, v92, 1.0
	v_fmac_f32_e32 v92, v94, v92
	v_mul_f32_e32 v94, v93, v92
	v_fma_f32 v95, -v91, v94, v93
	v_fmac_f32_e32 v94, v95, v92
	v_fma_f32 v91, -v91, v94, v93
	v_div_fmas_f32 v91, v91, v92, v94
	v_div_fixup_f32 v90, v91, v90, 1.0
	v_pk_mul_f32 v[86:87], v[86:87], v[90:91] op_sel_hi:[1,0]
	v_pk_mul_f32 v[84:85], v[84:85], v[90:91] op_sel_hi:[1,0]
	v_pk_mul_f32 v[92:93], v[82:83], v[90:91] op_sel_hi:[1,0]
	v_pk_mul_f32 v[82:83], v[80:81], v[90:91] op_sel_hi:[1,0]
	v_cvt_pk_bf16_f32 v80, v84, v85
	v_cvt_pk_bf16_f32 v81, v86, v87
	v_cvt_pk_bf16_f32 v82, v82, v83
	v_cvt_pk_bf16_f32 v83, v92, v93
	global_store_dwordx4 v[88:89], v[80:83], off
	v_add_co_u32_e32 v72, vcc, s44, v112
	v_cvt_f32_u32_e32 v78, v227
	v_addc_co_u32_e32 v73, vcc, 0, v113, vcc
	v_fmamk_f32 v74, v78, 0x33000000, v213
	v_div_scale_f32 v75, s[28:29], v74, v74, 1.0
	v_rcp_f32_e32 v76, v75
	v_div_scale_f32 v77, vcc, 1.0, v74, 1.0
	v_fma_f32 v78, -v75, v76, 1.0
	v_fmac_f32_e32 v76, v78, v76
	v_mul_f32_e32 v78, v77, v76
	v_fma_f32 v79, -v75, v78, v77
	v_fmac_f32_e32 v78, v79, v76
	v_fma_f32 v75, -v75, v78, v77
	v_div_fmas_f32 v75, v75, v76, v78
	v_div_fixup_f32 v74, v75, v74, 1.0
	v_pk_mul_f32 v[70:71], v[70:71], v[74:75] op_sel_hi:[1,0]
	v_pk_mul_f32 v[68:69], v[68:69], v[74:75] op_sel_hi:[1,0]
	v_pk_mul_f32 v[76:77], v[66:67], v[74:75] op_sel_hi:[1,0]
	v_pk_mul_f32 v[66:67], v[64:65], v[74:75] op_sel_hi:[1,0]
	v_cvt_pk_bf16_f32 v64, v68, v69
	v_cvt_pk_bf16_f32 v65, v70, v71
	v_cvt_pk_bf16_f32 v66, v66, v67
	v_cvt_pk_bf16_f32 v67, v76, v77
	global_store_dwordx4 v[72:73], v[64:67], off
	v_add_co_u32_e32 v56, vcc, s13, v112
	s_mov_b32 s13, 0xa0000
	s_nop 0
	v_addc_co_u32_e32 v57, vcc, 0, v113, vcc
	v_cvt_f32_u32_e32 v62, v228
	v_fmamk_f32 v58, v62, 0x33000000, v213
	v_div_scale_f32 v59, s[28:29], v58, v58, 1.0
	v_rcp_f32_e32 v60, v59
	v_div_scale_f32 v61, vcc, 1.0, v58, 1.0
	v_fma_f32 v62, -v59, v60, 1.0
	v_fmac_f32_e32 v60, v62, v60
	v_mul_f32_e32 v62, v61, v60
	v_fma_f32 v63, -v59, v62, v61
	v_fmac_f32_e32 v62, v63, v60
	v_fma_f32 v59, -v59, v62, v61
	v_div_fmas_f32 v59, v59, v60, v62
	v_div_fixup_f32 v58, v59, v58, 1.0
	v_pk_mul_f32 v[54:55], v[54:55], v[58:59] op_sel_hi:[1,0]
	v_pk_mul_f32 v[52:53], v[52:53], v[58:59] op_sel_hi:[1,0]
	v_pk_mul_f32 v[60:61], v[50:51], v[58:59] op_sel_hi:[1,0]
	v_pk_mul_f32 v[50:51], v[48:49], v[58:59] op_sel_hi:[1,0]
	v_cvt_pk_bf16_f32 v48, v52, v53
	v_cvt_pk_bf16_f32 v49, v54, v55
	v_cvt_pk_bf16_f32 v50, v50, v51
	v_cvt_pk_bf16_f32 v51, v60, v61
	global_store_dwordx4 v[56:57], v[48:51], off
	v_add_co_u32_e32 v40, vcc, s46, v112
	v_cvt_f32_u32_e32 v46, v229
	v_addc_co_u32_e32 v41, vcc, 0, v113, vcc
	v_fmamk_f32 v42, v46, 0x33000000, v213
	v_div_scale_f32 v43, s[28:29], v42, v42, 1.0
	v_rcp_f32_e32 v44, v43
	v_div_scale_f32 v45, vcc, 1.0, v42, 1.0
	v_fma_f32 v46, -v43, v44, 1.0
	v_fmac_f32_e32 v44, v46, v44
	v_mul_f32_e32 v46, v45, v44
	v_fma_f32 v47, -v43, v46, v45
	v_fmac_f32_e32 v46, v47, v44
	v_fma_f32 v43, -v43, v46, v45
	v_div_fmas_f32 v43, v43, v44, v46
	v_div_fixup_f32 v42, v43, v42, 1.0
	v_pk_mul_f32 v[38:39], v[38:39], v[42:43] op_sel_hi:[1,0]
	v_pk_mul_f32 v[36:37], v[36:37], v[42:43] op_sel_hi:[1,0]
	v_pk_mul_f32 v[44:45], v[34:35], v[42:43] op_sel_hi:[1,0]
	v_pk_mul_f32 v[34:35], v[32:33], v[42:43] op_sel_hi:[1,0]
	v_cvt_pk_bf16_f32 v32, v36, v37
	v_cvt_pk_bf16_f32 v33, v38, v39
	v_cvt_pk_bf16_f32 v34, v34, v35
	v_cvt_pk_bf16_f32 v35, v44, v45
	global_store_dwordx4 v[40:41], v[32:35], off
	v_add_co_u32_e32 v24, vcc, s13, v112
	v_cvt_f32_u32_e32 v30, v230
	v_addc_co_u32_e32 v25, vcc, 0, v113, vcc
	v_fmamk_f32 v26, v30, 0x33000000, v213
	v_div_scale_f32 v27, s[28:29], v26, v26, 1.0
	v_rcp_f32_e32 v28, v27
	v_div_scale_f32 v29, vcc, 1.0, v26, 1.0
	v_fma_f32 v30, -v27, v28, 1.0
	v_fmac_f32_e32 v28, v30, v28
	v_mul_f32_e32 v30, v29, v28
	v_fma_f32 v31, -v27, v30, v29
	v_fmac_f32_e32 v30, v31, v28
	v_fma_f32 v27, -v27, v30, v29
	v_div_fmas_f32 v27, v27, v28, v30
	v_div_fixup_f32 v26, v27, v26, 1.0
	v_pk_mul_f32 v[22:23], v[22:23], v[26:27] op_sel_hi:[1,0]
	v_pk_mul_f32 v[20:21], v[20:21], v[26:27] op_sel_hi:[1,0]
	v_pk_mul_f32 v[28:29], v[18:19], v[26:27] op_sel_hi:[1,0]
	v_pk_mul_f32 v[18:19], v[16:17], v[26:27] op_sel_hi:[1,0]
	v_cvt_pk_bf16_f32 v16, v20, v21
	v_cvt_pk_bf16_f32 v17, v22, v23
	v_cvt_pk_bf16_f32 v18, v18, v19
	v_cvt_pk_bf16_f32 v19, v28, v29
	global_store_dwordx4 v[24:25], v[16:19], off
	v_cvt_f32_u32_e32 v12, v231
	v_fmamk_f32 v9, v12, 0x33000000, v213
	v_div_scale_f32 v8, s[28:29], v9, v9, 1.0
	v_rcp_f32_e32 v10, v8
	v_div_scale_f32 v11, vcc, 1.0, v9, 1.0
	v_fma_f32 v12, -v8, v10, 1.0
	v_fmac_f32_e32 v10, v12, v10
	v_mul_f32_e32 v12, v11, v10
	v_fma_f32 v13, -v8, v12, v11
	v_fmac_f32_e32 v12, v13, v10
	v_fma_f32 v8, -v8, v12, v11
	v_div_fmas_f32 v10, v8, v10, v12
	v_add_co_u32_e32 v8, vcc, 0xb0000, v112
	v_div_fixup_f32 v10, v10, v9, 1.0
	s_nop 0
	v_addc_co_u32_e32 v9, vcc, 0, v113, vcc
	v_pk_mul_f32 v[6:7], v[6:7], v[10:11] op_sel_hi:[1,0]
	v_pk_mul_f32 v[4:5], v[4:5], v[10:11] op_sel_hi:[1,0]
	v_pk_mul_f32 v[12:13], v[2:3], v[10:11] op_sel_hi:[1,0]
	v_pk_mul_f32 v[2:3], v[0:1], v[10:11] op_sel_hi:[1,0]
	s_andn2_b64 vcc, exec, s[18:19]
	v_cvt_pk_bf16_f32 v0, v4, v5
	v_cvt_pk_bf16_f32 v1, v6, v7
	v_cvt_pk_bf16_f32 v2, v2, v3
	v_cvt_pk_bf16_f32 v3, v12, v13
	s_mov_b64 s[18:19], -1
	global_store_dwordx4 v[8:9], v[0:3], off
	s_cbranch_vccnz .LBB0_133
	s_andn2_b64 vcc, exec, s[0:1]
	s_cbranch_vccnz .LBB0_132
	s_barrier
	s_branch .LBB0_132
